# best GEMM handoff version plus counted waits in the attention P.V tail (four LDS reads issued together into dead registers instead of read-wait-MFMA x4)
# speedup vs baseline: 1.0095x; 1.0047x over previous
; #define LAS __attribute__((address_space(3)))
; __device__ __forceinline__ unsigned pk2(float lo, float hi) { return pg8::cvt_pk_bf16(lo, hi); }
; __device__ __forceinline__ void attn_phase(LAS unsigned char* lds, const bf16* QK, const bf16* VT, bf16* O, const float* sink) {
;     ...
;             float ps = 0.f;
; #pragma unroll
;             for (int r = 0; r < 16; ++r) { s0[r] = __builtin_amdgcn_exp2f(s0[r] - m); s1[r] = __builtin_amdgcn_exp2f(s1[r] - m); ps += s0[r] + s1[r]; }
;             l += ps;
; #pragma unroll
;             for (int ks = 0; ks < 4; ++ks) {
;                 v4u pw;
;                 if (ks < 2) { const int q0 = 8 * (ks & 1); pw.x = pk2(s0[q0], s0[q0 + 1]); pw.y = pk2(s0[q0 + 2], s0[q0 + 3]); pw.z = pk2(s0[q0 + 4], s0[q0 + 5]); pw.w = pk2(s0[q0 + 6], s0[q0 + 7]); }
;                 else { const int q0 = 8 * (ks & 1); pw.x = pk2(s1[q0], s1[q0 + 1]); pw.y = pk2(s1[q0 + 2], s1[q0 + 3]); pw.z = pk2(s1[q0 + 4], s1[q0 + 5]); pw.w = pk2(s1[q0 + 6], s1[q0 + 7]); }
;                 const bf16x8 pb = __builtin_bit_cast(bf16x8, pw);
; #pragma unroll
;                 for (int db = 0; db < 4; ++db) {
;                     const bf16x8 vf = *(const LAS bf16x8*)(vb + (32 * db + r32) * VROW + (2 * ks + hi) * 16);
;                     o[db] = __builtin_amdgcn_mfma_f32_32x32x16_bf16(vf, pb, o[db], 0, 0, 0);
;                 }
;             }
.LBB0_980:
	v_sub_f32_e32 v82, v82, v159
	v_sub_f32_e32 v66, v66, v159
	v_exp_f32_e32 v82, v82
	v_exp_f32_e32 v161, v66
	v_sub_f32_e32 v66, v83, v159
	v_sub_f32_e32 v67, v67, v159
	v_exp_f32_e32 v66, v66
	v_exp_f32_e32 v184, v67
	v_add_f32_e32 v67, v82, v161
	v_mov_b32_e32 v185, v1
	v_cvt_pk_bf16_f32 v82, v82, v66
	v_pk_add_f32 v[186:187], v[66:67], v[184:185]
	v_sub_f32_e32 v67, v84, v159
	v_exp_f32_e32 v185, v67
	v_sub_f32_e32 v67, v85, v159
	v_exp_f32_e32 v188, v67
	v_sub_f32_e32 v67, v86, v159
	v_exp_f32_e32 v191, v67
	v_sub_f32_e32 v67, v87, v159
	v_exp_f32_e32 v190, v67
	v_sub_f32_e32 v67, v88, v159
	v_sub_f32_e32 v66, v68, v159
	v_exp_f32_e32 v193, v67
	v_sub_f32_e32 v67, v89, v159
	v_add3_u32 v198, s10, v176, v178
	v_pk_add_f32 v[186:187], v[186:187], v[186:187] op_sel_hi:[0,1]
	v_exp_f32_e32 v195, v66
	v_sub_f32_e32 v66, v69, v159
	v_exp_f32_e32 v192, v67
	v_cvt_pk_bf16_f32 v83, v185, v188
	v_cvt_pk_bf16_f32 v84, v191, v190
	v_cvt_pk_bf16_f32 v85, v193, v192
	ds_read_b128 v[86:89], v198 offset:17408
	v_exp_f32_e32 v186, v66
	v_sub_f32_e32 v66, v90, v159
	v_exp_f32_e32 v197, v66
	ds_read_b128 v[66:69], v198 offset:22016
	s_waitcnt lgkmcnt(1)
	v_mfma_f32_32x32x16_bf16 v[50:65], v[86:89], v[82:85], v[50:65]
	v_sub_f32_e32 v86, v91, v159
	v_exp_f32_e32 v194, v86
	v_sub_f32_e32 v86, v92, v159
	v_exp_f32_e32 v199, v86
	v_sub_f32_e32 v86, v93, v159
	v_exp_f32_e32 v196, v86
	ds_read_b128 v[86:89], v198 offset:26624
	s_waitcnt lgkmcnt(1)
	v_mfma_f32_32x32x16_bf16 v[34:49], v[66:69], v[82:85], v[34:49]
	v_sub_f32_e32 v66, v94, v159
	v_exp_f32_e32 v200, v66
	v_sub_f32_e32 v66, v95, v159
	v_exp_f32_e32 v94, v66
	v_sub_f32_e32 v66, v96, v159
	v_exp_f32_e32 v201, v66
	ds_read_b128 v[66:69], v198 offset:31232
	s_waitcnt lgkmcnt(1)
	v_mfma_f32_32x32x16_bf16 v[18:33], v[86:89], v[82:85], v[18:33]
	v_sub_f32_e32 v86, v97, v159
	v_exp_f32_e32 v96, v86
	v_cvt_pk_bf16_f32 v86, v197, v194
	v_cvt_pk_bf16_f32 v87, v199, v196
	v_cvt_pk_bf16_f32 v88, v200, v94
	v_cvt_pk_bf16_f32 v89, v201, v96
	ds_read_b128 v[90:93], v198 offset:17440
	s_waitcnt lgkmcnt(1)
	v_mfma_f32_32x32x16_bf16 v[2:17], v[66:69], v[82:85], v[2:17]
	ds_read_b128 v[66:69], v198 offset:22048
	v_add_f32_e32 v189, v185, v195
	v_add_f32_e64 v82, v188, v186
	v_add_f32_e64 v83, v189, v187
	v_sub_f32_e32 v70, v70, v159
	v_pk_add_f32 v[188:189], v[82:83], v[82:83] op_sel_hi:[0,1]
	v_exp_f32_e32 v95, v70
	v_sub_f32_e32 v70, v71, v159
	v_exp_f32_e32 v188, v70
	ds_read_b128 v[82:85], v198 offset:26656
	v_add_f32_e32 v191, v191, v95
	s_waitcnt lgkmcnt(2)
	v_mfma_f32_32x32x16_bf16 v[50:65], v[90:93], v[86:89], v[50:65]
	v_add_f32_e64 v70, v190, v188
	v_add_f32_e64 v71, v191, v189
	v_sub_f32_e32 v74, v74, v159
	v_add_f32_e64 v90, v70, v70
	v_add_f32_e64 v91, v70, v71
	v_sub_f32_e32 v70, v72, v159
	v_exp_f32_e32 v97, v70
	v_sub_f32_e32 v76, v76, v159
	v_add_f32_e32 v193, v193, v97
	s_waitcnt lgkmcnt(1)
	v_mfma_f32_32x32x16_bf16 v[34:49], v[66:69], v[86:89], v[34:49]
	v_sub_f32_e32 v66, v73, v159
	v_exp_f32_e32 v90, v66
	ds_read_b128 v[66:69], v198 offset:31264
	v_pk_add_f32 v[70:71], v[192:193], v[90:91]
	s_nop 0
	v_pk_add_f32 v[92:93], v[70:71], v[70:71] op_sel_hi:[0,1]
	s_waitcnt lgkmcnt(1)
	v_mfma_f32_32x32x16_bf16 v[18:33], v[82:85], v[86:89], v[18:33]
	v_cvt_pk_bf16_f32 v70, v161, v184
	v_cvt_pk_bf16_f32 v71, v195, v186
	v_cvt_pk_bf16_f32 v72, v95, v188
	v_cvt_pk_bf16_f32 v73, v97, v90
	ds_read_b128 v[82:85], v198 offset:17472
	s_waitcnt lgkmcnt(1)
	v_mfma_f32_32x32x16_bf16 v[2:17], v[66:69], v[86:89], v[2:17]
	v_exp_f32_e32 v86, v74
	v_sub_f32_e32 v66, v75, v159
	v_exp_f32_e32 v92, v66
	ds_read_b128 v[66:69], v198 offset:22080
	v_add_f32_e32 v195, v197, v86
	v_exp_f32_e32 v87, v76
	v_pk_add_f32 v[74:75], v[194:195], v[92:93]
	s_waitcnt lgkmcnt(1)
	v_mfma_f32_32x32x16_bf16 v[50:65], v[82:85], v[70:73], v[50:65]
	v_add_f32_e64 v82, v74, v74
	v_add_f32_e64 v83, v74, v75
	v_sub_f32_e32 v74, v77, v159
	v_exp_f32_e32 v82, v74
	v_add_f32_e32 v197, v199, v87
	ds_read_b128 v[74:77], v198 offset:26688
	s_waitcnt lgkmcnt(1)
	v_mfma_f32_32x32x16_bf16 v[34:49], v[66:69], v[70:73], v[34:49]
	v_add_f32_e64 v66, v196, v82
	v_add_f32_e64 v67, v197, v83
	v_add_f32_e64 v84, v66, v66
	v_add_f32_e64 v85, v66, v67
	v_sub_f32_e32 v66, v78, v159
	v_exp_f32_e32 v78, v66
	v_sub_f32_e32 v66, v79, v159
	v_exp_f32_e32 v84, v66
	ds_read_b128 v[66:69], v198 offset:31296
	v_add_f32_e32 v95, v200, v78
	s_waitcnt lgkmcnt(1)
	v_mfma_f32_32x32x16_bf16 v[18:33], v[74:77], v[70:73], v[18:33]
	v_add_f32_e64 v74, v94, v84
	v_add_f32_e64 v75, v95, v85
	v_pk_add_f32 v[74:75], v[74:75], v[74:75] op_sel_hi:[0,1]
	v_sub_f32_e32 v74, v80, v159
	v_exp_f32_e32 v76, v74
	v_sub_f32_e32 v74, v81, v159
	v_exp_f32_e32 v74, v74
	s_waitcnt lgkmcnt(0)
	v_mfma_f32_32x32x16_bf16 v[2:17], v[66:69], v[70:73], v[2:17]
	v_cvt_pk_bf16_f32 v66, v86, v92
	v_cvt_pk_bf16_f32 v67, v87, v82
	v_cvt_pk_bf16_f32 v68, v78, v84
	v_cvt_pk_bf16_f32 v69, v76, v74
	ds_read_b128 v[70:73], v198 offset:17504
	ds_read_b128 v[230:233], v198 offset:22112
	ds_read_b128 v[234:237], v198 offset:26720
	ds_read_b128 v[238:241], v198 offset:31328
	v_add_f32_e32 v97, v201, v76
	v_add_f32_e64 v74, v96, v74
	v_add_f32_e64 v75, v97, v75
	s_waitcnt lgkmcnt(3)
	v_mfma_f32_32x32x16_bf16 v[50:65], v[70:73], v[66:69], v[50:65]
	v_add_f32_e32 v74, v74, v75
	v_add_f32_e32 v157, v157, v74
	s_waitcnt lgkmcnt(2)
	v_mfma_f32_32x32x16_bf16 v[34:49], v[230:233], v[66:69], v[34:49]
	s_waitcnt lgkmcnt(1)
	v_mfma_f32_32x32x16_bf16 v[18:33], v[234:237], v[66:69], v[18:33]
	s_waitcnt lgkmcnt(0)
	v_mfma_f32_32x32x16_bf16 v[2:17], v[238:241], v[66:69], v[2:17]
	s_andn2_b64 vcc, exec, s[6:7]
	s_cbranch_vccz .LBB0_969
	s_branch .LBB0_970
